# norm0 row loop: the loop-top vmcnt(0) (which waited on the previous row's store acks) moved out of the loop; stores now drain under the next row's reduction
# speedup vs baseline: 1.0115x; 1.0115x over previous
.LBB0_661:
	s_getreg_b32 s0, hwreg(HW_REG_HW_ID, 0, 6)
	s_lshl_b32 s0, s0, 2
	s_and_b32 s0, s0, 0xfc
	s_add_i32 s1, 0, 0x256c0
	s_add_i32 s0, s1, s0
	v_mov_b32_e32 v0, s0
	ds_read_b32 v0, v0
	v_mbcnt_lo_u32_b32 v1, -1, 0
	v_mbcnt_hi_u32_b32 v1, -1, v1
	s_getreg_b32 s0, hwreg(HW_REG_HW_ID, 0, 6)
	s_lshl_b32 s0, s0, 2
	s_and_b32 s0, s0, 0xfc
	s_waitcnt lgkmcnt(0)
	v_readfirstlane_b32 s3, v0
	s_add_i32 s0, s1, s0
	s_nop 0
	v_lshl_add_u32 v0, s3, 6, v1
	v_mov_b32_e32 v1, s0
	ds_read_b32 v1, v1
	v_ashrrev_i32_e32 v0, 6, v0
	v_lshl_add_u32 v28, s2, 3, v0
	s_mov_b32 s3, 0x8800
	v_cmp_gt_i32_e32 vcc, s3, v28
	v_mbcnt_lo_u32_b32 v20, -1, 0
	v_mbcnt_hi_u32_b32 v20, -1, v20
	s_and_saveexec_b64 s[0:1], vcc
	s_cbranch_execz .LBB0_664
	s_mov_b32 s14, 0x8000
	v_add_u32_e32 v0, 0xffff8000, v28
	v_ashrrev_i32_e32 v29, 31, v28
	v_cmp_gt_i32_e32 vcc, s14, v28
	v_mov_b32_e32 v2, s57
	v_mov_b32_e32 v3, s53
	s_waitcnt lgkmcnt(0)
	v_cndmask_b32_e32 v1, 0, v29, vcc
	v_cndmask_b32_e32 v0, v0, v28, vcc
	v_cndmask_b32_e32 v3, v2, v3, vcc
	v_mov_b32_e32 v2, s56
	v_mov_b32_e32 v4, s52
	v_cndmask_b32_e32 v2, v2, v4, vcc
	v_lshlrev_b64 v[0:1], 12, v[0:1]
	v_lshl_add_u64 v[0:1], v[2:3], 0, v[0:1]
	v_lshlrev_b32_e32 v2, 2, v20
	v_and_b32_e32 v22, 0xfc, v2
	v_mov_b32_e32 v17, 0
	v_lshlrev_b32_e32 v16, 2, v22
	v_lshl_add_u64 v[18:19], v[0:1], 0, v[16:17]
	global_load_dwordx4 v[12:15], v[18:19], off
	global_load_dwordx4 v[8:11], v[18:19], off offset:1024
	global_load_dwordx4 v[4:7], v[18:19], off offset:2048
	global_load_dwordx4 v[0:3], v[18:19], off offset:3072
	v_mbcnt_lo_u32_b32 v18, -1, 0
	v_mbcnt_hi_u32_b32 v18, -1, v18
	v_and_b32_e32 v19, 64, v18
	v_add_u32_e32 v19, 64, v19
	v_xor_b32_e32 v21, 1, v18
	v_cmp_lt_i32_e32 vcc, v21, v19
	s_load_dword s6, s[90:91], 0x0
	s_add_u32 s4, s78, 0x1500000
	v_cndmask_b32_e32 v21, v18, v21, vcc
	v_lshlrev_b32_e32 v30, 2, v21
	v_xor_b32_e32 v21, 2, v18
	v_cmp_lt_i32_e32 vcc, v21, v19
	v_lshlrev_b64 v[38:39], 11, v[28:29]
	s_addc_u32 s5, s79, 0
	v_cndmask_b32_e32 v21, v18, v21, vcc
	v_lshlrev_b32_e32 v31, 2, v21
	v_xor_b32_e32 v21, 4, v18
	v_cmp_lt_i32_e32 vcc, v21, v19
	s_waitcnt lgkmcnt(0)
	s_lshl_b32 s6, s6, 3
	v_or_b32_e32 v24, 0x100, v22
	v_cndmask_b32_e32 v21, v18, v21, vcc
	v_lshlrev_b32_e32 v32, 2, v21
	v_xor_b32_e32 v21, 8, v18
	v_cmp_lt_i32_e32 vcc, v21, v19
	v_or_b32_e32 v26, 0x200, v22
	v_or_b32_e32 v36, 0x300, v22
	v_cndmask_b32_e32 v21, v18, v21, vcc
	v_lshlrev_b32_e32 v33, 2, v21
	v_xor_b32_e32 v21, 16, v18
	v_cmp_lt_i32_e32 vcc, v21, v19
	s_mov_b64 s[8:9], 0x4000000
	s_ashr_i32 s7, s6, 31
	v_cndmask_b32_e32 v21, v18, v21, vcc
	v_lshlrev_b32_e32 v34, 2, v21
	v_xor_b32_e32 v21, 32, v18
	v_cmp_lt_i32_e32 vcc, v21, v19
	s_mov_b64 s[10:11], 0
	s_mov_b64 s[12:13], 0x1000
	v_cndmask_b32_e32 v18, v18, v21, vcc
	v_lshlrev_b32_e32 v35, 2, v18
	v_lshl_add_u64 v[18:19], s[64:65], 0, v[16:17]
	v_and_b32_e32 v16, 63, v20
	v_lshl_or_b32 v38, v16, 3, v38
	v_lshl_add_u64 v[20:21], s[78:79], 0, v[38:39]
	v_lshl_add_u64 v[20:21], v[20:21], 0, s[8:9]
	s_lshl_b64 s[8:9], s[6:7], 11
	s_mov_b32 s7, 0x87ff
	v_lshlrev_b32_e32 v16, 2, v22
	v_mov_b32_e32 v29, 0x358637bd
	s_mov_b32 s15, 0x800000
	v_lshlrev_b32_e32 v22, 2, v24
	v_lshlrev_b32_e32 v24, 2, v26
	v_lshlrev_b32_e32 v26, 2, v36
	s_waitcnt vmcnt(0)
.LBB0_663:
	v_add_u32_e32 v74, s6, v28
	v_min_i32_e32 v56, 0x8000, v28
	v_cmp_gt_i32_e32 vcc, s3, v74
	v_pk_mul_f32 v[40:41], v[2:3], v[2:3]
	v_pk_mul_f32 v[42:43], v[6:7], v[6:7]
	v_pk_mul_f32 v[44:45], v[0:1], v[0:1]
	v_pk_mul_f32 v[46:47], v[4:5], v[4:5]
	v_pk_mul_f32 v[48:49], v[14:15], v[14:15]
	v_pk_mul_f32 v[50:51], v[10:11], v[10:11]
	v_pk_mul_f32 v[52:53], v[12:13], v[12:13]
	v_pk_mul_f32 v[54:55], v[8:9], v[8:9]
	v_cndmask_b32_e32 v28, v28, v74, vcc
	v_ashrrev_i32_e32 v60, 12, v56
	v_mov_b32_e32 v56, v52
	v_mov_b32_e32 v57, v54
	v_mov_b32_e32 v54, v53
	v_mov_b32_e32 v52, v48
	v_mov_b32_e32 v53, v50
	v_mov_b32_e32 v50, v49
	v_mov_b32_e32 v48, v44
	v_mov_b32_e32 v49, v46
	v_mov_b32_e32 v46, v45
	v_mov_b32_e32 v44, v40
	v_mov_b32_e32 v45, v42
	v_mov_b32_e32 v42, v41
	v_add_u32_e32 v41, 0xffff8000, v28
	v_mul_i32_i24_e32 v40, 0xc00, v60
	v_cmp_gt_i32_e32 vcc, s14, v28
	v_pk_add_f32 v[46:47], v[48:49], v[46:47]
	global_load_dwordx4 v[36:39], v[18:19], off
	global_load_dwordx4 v[140:143], v[18:19], off offset:1024
	global_load_dwordx4 v[144:147], v[18:19], off offset:2048
	global_load_dwordx4 v[148:151], v[18:19], off offset:3072
	v_cndmask_b32_e32 v48, v41, v28, vcc
	v_ashrrev_i32_e32 v41, 31, v40
	v_lshl_add_u64 v[40:41], v[40:41], 2, s[4:5]
	v_pk_add_f32 v[44:45], v[44:45], v[46:47]
	v_lshl_add_u64 v[66:67], v[40:41], 0, s[12:13]
	v_pk_add_f32 v[64:65], v[42:43], v[44:45]
	v_lshl_add_u64 v[68:69], v[40:41], 0, v[16:17]
	v_lshl_add_u64 v[44:45], v[66:67], 0, v[16:17]
	global_load_dwordx4 v[40:43], v[68:69], off
	global_load_dwordx4 v[152:155], v[68:69], off offset:1024
	global_load_dwordx4 v[156:159], v[68:69], off offset:2048
	global_load_dwordx4 v[160:163], v[68:69], off offset:3072
	s_nop 0
	global_load_dwordx4 v[164:167], v[44:45], off offset:1024
	global_load_dwordx4 v[168:171], v[44:45], off offset:2048
	global_load_dwordx4 v[172:175], v[44:45], off offset:3072
	global_load_dwordx4 v[44:47], v[44:45], off
	v_pk_add_f32 v[54:55], v[56:57], v[54:55]
	v_mov_b32_e32 v25, s57
	v_pk_add_f32 v[52:53], v[52:53], v[54:55]
	v_mov_b32_e32 v27, s53
	v_pk_add_f32 v[50:51], v[50:51], v[52:53]
	v_cndmask_b32_e32 v57, v25, v27, vcc
	v_add_f32_e32 v25, v50, v51
	v_mov_b32_e32 v23, v17
	v_add_f32_e32 v25, v65, v25
	v_lshl_add_u64 v[72:73], v[66:67], 0, v[22:23]
	v_add_f32_e32 v23, v64, v25
	ds_bpermute_b32 v25, v30, v23
	v_mov_b32_e32 v58, s56
	v_mov_b32_e32 v59, s52
	v_ashrrev_i32_e32 v61, 31, v28
	v_cndmask_b32_e32 v49, 0, v61, vcc
	s_waitcnt lgkmcnt(0)
	v_add_f32_e32 v23, v23, v25
	ds_bpermute_b32 v25, v31, v23
	v_cndmask_b32_e32 v56, v58, v59, vcc
	v_lshlrev_b64 v[48:49], 12, v[48:49]
	v_lshl_add_u64 v[48:49], v[56:57], 0, v[48:49]
	v_lshl_add_u64 v[70:71], v[48:49], 0, v[16:17]
	s_waitcnt lgkmcnt(0)
	v_add_f32_e32 v23, v23, v25
	ds_bpermute_b32 v25, v32, v23
	global_load_dwordx4 v[48:51], v[70:71], off nt
	global_load_dwordx4 v[52:55], v[70:71], off offset:1024 nt
	global_load_dwordx4 v[56:59], v[70:71], off offset:2048 nt
	global_load_dwordx4 v[60:63], v[70:71], off offset:3072 nt
	v_mov_b32_e32 v27, v17
	v_mov_b32_e32 v28, v74
	s_waitcnt lgkmcnt(0)
	v_add_f32_e32 v23, v23, v25
	ds_bpermute_b32 v25, v33, v23
	s_waitcnt lgkmcnt(0)
	v_add_f32_e32 v23, v23, v25
	ds_bpermute_b32 v25, v34, v23
	s_waitcnt lgkmcnt(0)
	v_add_f32_e32 v23, v23, v25
	ds_bpermute_b32 v25, v35, v23
	s_waitcnt lgkmcnt(0)
	v_add_f32_e32 v23, v23, v25
	v_fmamk_f32 v23, v23, 0x3a800000, v29
	v_mul_f32_e32 v25, 0x4b800000, v23
	v_cmp_gt_f32_e32 vcc, s15, v23
	s_nop 1
	v_cndmask_b32_e32 v23, v23, v25, vcc
	v_rsq_f32_e32 v23, v23
	s_nop 0
	v_mul_f32_e32 v25, 0x45800000, v23
	v_cndmask_b32_e32 v64, v23, v25, vcc
	v_pk_mul_f32 v[12:13], v[12:13], v[64:65] op_sel_hi:[1,0]
	v_pk_mul_f32 v[14:15], v[14:15], v[64:65] op_sel_hi:[1,0]
	v_pk_mul_f32 v[8:9], v[8:9], v[64:65] op_sel_hi:[1,0]
	v_pk_mul_f32 v[10:11], v[10:11], v[64:65] op_sel_hi:[1,0]
	v_mov_b32_e32 v25, v17
	v_pk_mul_f32 v[4:5], v[4:5], v[64:65] op_sel_hi:[1,0]
	v_pk_mul_f32 v[6:7], v[6:7], v[64:65] op_sel_hi:[1,0]
	v_cmp_lt_i32_e32 vcc, s7, v74
	s_or_b64 s[10:11], vcc, s[10:11]
	s_waitcnt vmcnt(4)
	v_pk_mul_f32 v[12:13], v[36:37], v[12:13]
	v_pk_mul_f32 v[14:15], v[38:39], v[14:15]
	v_pk_add_f32 v[36:37], v[44:45], 1.0 op_sel_hi:[1,0]
	v_pk_add_f32 v[38:39], v[46:47], 1.0 op_sel_hi:[1,0]
	v_pk_fma_f32 v[12:13], v[36:37], v[12:13], v[40:41]
	v_pk_fma_f32 v[14:15], v[38:39], v[14:15], v[42:43]
	v_cvt_pk_bf16_f32 v12, v12, v13
	v_cvt_pk_bf16_f32 v13, v14, v15
	global_store_dwordx2 v[20:21], v[12:13], off
	s_nop 0
	v_lshl_add_u64 v[44:45], v[66:67], 0, v[24:25]
	v_lshl_add_u64 v[66:67], v[66:67], 0, v[26:27]
	v_pk_mul_f32 v[8:9], v[140:141], v[8:9]
	v_pk_add_f32 v[12:13], v[164:165], 1.0 op_sel_hi:[1, 0]
	v_pk_mul_f32 v[10:11], v[142:143], v[10:11]
	v_pk_add_f32 v[14:15], v[166:167], 1.0 op_sel_hi:[1, 0]
	v_pk_fma_f32 v[8:9], v[12:13], v[8:9], v[152:153]
	v_pk_fma_f32 v[10:11], v[14:15], v[10:11], v[154:155]
	v_cvt_pk_bf16_f32 v8, v8, v9
	v_cvt_pk_bf16_f32 v9, v10, v11
	global_store_dwordx2 v[20:21], v[8:9], off offset:512
	s_nop 0
	v_pk_mul_f32 v[4:5], v[144:145], v[4:5]
	v_pk_add_f32 v[8:9], v[168:169], 1.0 op_sel_hi:[1, 0]
	v_pk_mul_f32 v[6:7], v[146:147], v[6:7]
	v_pk_add_f32 v[10:11], v[170:171], 1.0 op_sel_hi:[1, 0]
	v_pk_fma_f32 v[4:5], v[4:5], v[8:9], v[156:157]
	v_pk_fma_f32 v[6:7], v[6:7], v[10:11], v[158:159]
	v_cvt_pk_bf16_f32 v4, v4, v5
	v_cvt_pk_bf16_f32 v5, v6, v7
	global_store_dwordx2 v[20:21], v[4:5], off offset:1024
	v_pk_mul_f32 v[66:67], v[0:1], v[64:65] op_sel_hi:[1,0]
	v_pk_mul_f32 v[64:65], v[2:3], v[64:65] op_sel_hi:[1,0]
	s_waitcnt vmcnt(3)
	v_mov_b32_e32 v12, v48
	v_mov_b32_e32 v13, v49
	v_mov_b32_e32 v14, v50
	v_mov_b32_e32 v15, v51
	v_mov_b32_e32 v8, v52
	v_mov_b32_e32 v9, v53
	v_mov_b32_e32 v10, v54
	v_mov_b32_e32 v11, v55
	v_mov_b32_e32 v4, v56
	v_mov_b32_e32 v5, v57
	v_mov_b32_e32 v6, v58
	v_mov_b32_e32 v7, v59
	v_mov_b32_e32 v0, v60
	v_mov_b32_e32 v1, v61
	v_mov_b32_e32 v2, v62
	v_mov_b32_e32 v3, v63
	v_pk_mul_f32 v[36:37], v[66:67], v[148:149]
	v_pk_add_f32 v[40:41], v[172:173], 1.0 op_sel_hi:[1, 0]
	v_pk_mul_f32 v[38:39], v[64:65], v[150:151]
	v_pk_add_f32 v[42:43], v[174:175], 1.0 op_sel_hi:[1, 0]
	v_pk_fma_f32 v[36:37], v[36:37], v[40:41], v[160:161]
	v_pk_fma_f32 v[38:39], v[38:39], v[42:43], v[162:163]
	v_cvt_pk_bf16_f32 v36, v36, v37
	v_cvt_pk_bf16_f32 v37, v38, v39
	global_store_dwordx2 v[20:21], v[36:37], off offset:1536
	v_lshl_add_u64 v[20:21], v[20:21], 0, s[8:9]
	s_andn2_b64 exec, exec, s[10:11]
	s_cbranch_execnz .LBB0_663
